# row pass: next row's loads stay in flight across this row's arithmetic (counted wait after the row's stores instead of vmcnt(0) right after issue; store-ack waits in front of the F loads removed)
# speedup vs baseline: 1.0219x; 1.0219x over previous
.LBB0_494:
	s_or_b64 exec, exec, s[0:1]
	v_and_b32_e32 v21, 64, v156
	v_add_u32_e32 v21, 64, v21
	v_xor_b32_e32 v22, 1, v156
	v_readlane_b32 s50, v232, 0
	v_cmp_lt_i32_e32 vcc, v22, v21
	v_readlane_b32 s51, v232, 1
	v_readlane_b32 s52, v232, 15
	v_cndmask_b32_e32 v22, v156, v22, vcc
	s_cmp_lg_u64 s[50:51], 0
	v_readlane_b32 s53, v232, 16
	v_lshlrev_b32_e32 v61, 2, v22
	v_xor_b32_e32 v22, 2, v156
	s_cselect_b64 s[72:73], -1, 0
	s_cmp_lg_u64 s[52:53], 0
	v_cmp_lt_i32_e32 vcc, v22, v21
	s_cselect_b64 s[74:75], -1, 0
	s_lshl_b64 s[0:1], s[8:9], 2
	v_cndmask_b32_e32 v22, v156, v22, vcc
	v_lshlrev_b32_e32 v90, 2, v22
	v_xor_b32_e32 v22, 4, v156
	s_add_u32 s46, s0, 0x12c00000
	v_cmp_lt_i32_e32 vcc, v22, v21
	s_addc_u32 s48, s1, 0
	s_lshl_b64 s[0:1], s[8:9], 11
	v_cndmask_b32_e32 v22, v156, v22, vcc
	s_add_u32 s0, s52, s0
	v_lshlrev_b32_e32 v91, 2, v22
	v_xor_b32_e32 v22, 8, v156
	s_addc_u32 s1, s53, s1
	v_cmp_lt_i32_e32 vcc, v22, v21
	v_lshl_add_u64 v[50:51], s[0:1], 0, v[96:97]
	s_lshl_b64 s[0:1], s[8:9], 12
	v_cndmask_b32_e32 v22, v156, v22, vcc
	s_add_u32 s76, s50, s0
	v_lshlrev_b32_e32 v92, 2, v22
	v_xor_b32_e32 v22, 16, v156
	s_addc_u32 s77, s51, s1
	s_add_i32 s0, s64, s8
	v_cmp_lt_i32_e32 vcc, v22, v21
	s_ashr_i32 s1, s0, 31
	s_lshl_b64 s[50:51], s[0:1], 2
	v_cndmask_b32_e32 v22, v156, v22, vcc
	v_lshlrev_b32_e32 v93, 2, v22
	v_xor_b32_e32 v22, 32, v156
	s_add_u32 s9, s50, 0x12c00000
	v_cmp_lt_i32_e32 vcc, v22, v21
	s_addc_u32 s49, s51, 0
	s_lshl_b64 s[50:51], s[0:1], 11
	v_cndmask_b32_e32 v21, v156, v22, vcc
	v_or_b32_e32 v52, s50, v96
	v_mov_b32_e32 v53, s51
	s_lshl_b64 s[50:51], s[0:1], 6
	s_lshl_b64 s[0:1], s[0:1], 12
	v_lshlrev_b32_e32 v94, 2, v21
	v_mov_b32_e32 v21, v97
	s_add_u32 s78, s56, s0
	v_cmp_eq_u32_e64 s[42:43], 0, v159
	v_mov_b32_e32 v49, v97
	v_lshl_add_u64 v[54:55], s[50:51], 0, v[20:21]
	s_addc_u32 s79, s57, s1
	s_waitcnt vmcnt(0)
	s_branch .LBB0_497
.Lrow_noxn:
	s_and_b64 vcc, exec, s[72:73]
	s_cbranch_vccnz .LBB0_496
	s_waitcnt vmcnt(0)
	s_branch .LBB0_496

.LBB0_500:
	v_readlane_b32 s52, v233, 5
	v_readlane_b32 s56, v233, 9
	v_readlane_b32 s57, v233, 10
	v_mov_b32_e32 v56, 0
	v_mov_b32_e32 v95, 0
	s_andn2_b64 vcc, exec, s[0:1]
	v_lshl_add_u64 v[82:83], s[56:57], 0, v[52:53]
	v_mov_b32_e32 v98, 0
	v_mov_b32_e32 v57, 0
	v_mov_b32_e32 v66, 0
	v_mov_b32_e32 v67, 0
	v_mov_b32_e32 v68, 0
	v_mov_b32_e32 v69, 0
	v_mov_b32_e32 v64, 0
	v_mov_b32_e32 v65, 0
	v_readlane_b32 s53, v233, 6
	v_readlane_b32 s54, v233, 7
	v_readlane_b32 s55, v233, 8
	v_readlane_b32 s58, v233, 11
	v_readlane_b32 s59, v233, 12
	s_cbranch_vccnz .LBB0_502
	v_readlane_b32 s52, v233, 5
	v_add_co_u32_e32 v20, vcc, 0x5300000, v82
	v_readlane_b32 s56, v233, 9
	s_nop 0
	v_addc_co_u32_e32 v21, vcc, 0, v83, vcc
	v_readlane_b32 s57, v233, 10
	s_add_u32 s0, s56, s9
	global_load_dwordx2 v[56:57], v[20:21], off offset:1536
	s_addc_u32 s1, s57, s49
	global_load_dwordx2 v[64:65], v[20:21], off
	global_load_dwordx2 v[68:69], v[20:21], off offset:512
	global_load_dwordx2 v[66:67], v[20:21], off offset:1024
	global_load_dword v98, v97, s[0:1]
	v_mov_b32_e32 v40, 0
	v_mov_b32_e32 v41, v40
	v_mov_b32_e32 v42, v40
	v_mov_b32_e32 v43, v40
	v_mov_b32_e32 v32, v40
	v_mov_b32_e32 v33, v40
	v_mov_b32_e32 v34, v40
	v_mov_b32_e32 v35, v40
	v_mov_b32_e32 v28, v40
	v_mov_b32_e32 v29, v40
	v_mov_b32_e32 v30, v40
	v_mov_b32_e32 v31, v40
	v_mov_b32_e32 v20, v40
	v_mov_b32_e32 v21, v40
	v_mov_b32_e32 v22, v40
	v_mov_b32_e32 v23, v40
	v_readlane_b32 s53, v233, 6
	v_readlane_b32 s54, v233, 7
	v_readlane_b32 s55, v233, 8
	v_readlane_b32 s58, v233, 11
	v_readlane_b32 s59, v233, 12

.LBB0_506:
	ds_bpermute_b32 v96, v61, v99
	v_lshlrev_b32_e32 v100, 16, v80
	v_and_b32_e32 v101, 0xffff0000, v80
	v_lshlrev_b32_e32 v80, 16, v81
	v_and_b32_e32 v81, 0xffff0000, v81
	s_waitcnt lgkmcnt(0)
	v_add_f32_e32 v96, v99, v96
	ds_bpermute_b32 v99, v90, v96
	v_pk_mul_f32 v[80:81], v[60:61], v[80:81] op_sel_hi:[0,1]
	v_cndmask_b32_e64 v47, v47, v81, s[38:39]
	v_cndmask_b32_e64 v46, v46, v80, s[38:39]
	v_lshlrev_b32_e32 v80, 16, v78
	s_waitcnt lgkmcnt(0)
	v_add_f32_e32 v96, v96, v99
	ds_bpermute_b32 v99, v91, v96
	v_and_b32_e32 v81, 0xffff0000, v78
	v_pk_mul_f32 v[80:81], v[60:61], v[80:81] op_sel_hi:[0,1]
	v_cndmask_b32_e64 v81, v37, v81, s[38:39]
	v_cndmask_b32_e64 v80, v36, v80, s[38:39]
	v_lshlrev_b32_e32 v36, 16, v74
	v_and_b32_e32 v37, 0xffff0000, v74
	s_waitcnt lgkmcnt(0)
	v_add_f32_e32 v74, v96, v99
	ds_bpermute_b32 v96, v92, v74
	v_lshlrev_b32_e32 v78, 16, v79
	v_and_b32_e32 v79, 0xffff0000, v79
	v_pk_mul_f32 v[36:37], v[60:61], v[36:37] op_sel_hi:[0,1]
	v_pk_mul_f32 v[78:79], v[60:61], v[78:79] op_sel_hi:[0,1]
	s_waitcnt lgkmcnt(0)
	v_add_f32_e32 v96, v74, v96
	ds_bpermute_b32 v99, v93, v96
	v_cndmask_b32_e64 v74, v24, v36, s[38:39]
	v_cndmask_b32_e64 v79, v39, v79, s[38:39]
	v_cndmask_b32_e64 v78, v38, v78, s[38:39]
	v_lshlrev_b32_e32 v38, 16, v75
	s_waitcnt lgkmcnt(0)
	v_add_f32_e32 v36, v96, v99
	v_and_b32_e32 v39, 0xffff0000, v75
	v_cndmask_b32_e64 v75, v25, v37, s[38:39]
	ds_bpermute_b32 v37, v94, v36
	v_lshlrev_b32_e32 v24, 16, v72
	v_and_b32_e32 v25, 0xffff0000, v72
	v_pk_mul_f32 v[100:101], v[60:61], v[100:101] op_sel_hi:[0,1]
	v_pk_mul_f32 v[38:39], v[60:61], v[38:39] op_sel_hi:[0,1]
	s_waitcnt lgkmcnt(0)
	v_add_f32_e32 v36, v36, v37
	v_fmamk_f32 v36, v36, 0x3a800000, v153
	v_mul_f32_e32 v37, 0x4f800000, v36
	v_cmp_gt_f32_e32 vcc, s33, v36
	v_pk_mul_f32 v[24:25], v[60:61], v[24:25] op_sel_hi:[0,1]
	v_cndmask_b32_e64 v45, v45, v101, s[38:39]
	v_cndmask_b32_e32 v36, v36, v37, vcc
	v_sqrt_f32_e32 v37, v36
	v_cndmask_b32_e64 v44, v44, v100, s[38:39]
	v_cndmask_b32_e64 v101, v27, v39, s[38:39]
	v_cndmask_b32_e64 v100, v26, v38, s[38:39]
	v_lshlrev_b32_e32 v26, 16, v73
	v_and_b32_e32 v27, 0xffff0000, v73
	v_cndmask_b32_e64 v73, v17, v25, s[38:39]
	v_add_u32_e32 v17, -1, v37
	v_fma_f32 v25, -v17, v37, v36
	v_cmp_ge_f32_e64 s[0:1], 0, v25
	v_add_u32_e32 v25, 1, v37
	v_readlane_b32 s50, v233, 54
	v_cndmask_b32_e64 v17, v37, v17, s[0:1]
	v_fma_f32 v37, -v25, v37, v36
	v_cmp_lt_f32_e64 s[0:1], 0, v37
	v_cndmask_b32_e64 v72, v16, v24, s[38:39]
	v_pk_mul_f32 v[26:27], v[60:61], v[26:27] op_sel_hi:[0,1]
	v_cndmask_b32_e64 v17, v17, v25, s[0:1]
	v_mul_f32_e32 v25, 0x37800000, v17
	v_cndmask_b32_e32 v17, v17, v25, vcc
	v_cmp_class_f32_e32 vcc, v36, v154
	v_cndmask_b32_e64 v102, v18, v26, s[38:39]
	v_cndmask_b32_e64 v103, v19, v27, s[38:39]
	v_cndmask_b32_e32 v17, v17, v36, vcc
	v_div_scale_f32 v25, s[0:1], v17, v17, s50
	v_rcp_f32_e32 v36, v25
	s_nop 0
	v_fma_f32 v16, -v25, v36, 1.0
	v_fmac_f32_e32 v36, v16, v36
	v_div_scale_f32 v16, vcc, s50, v17, s50
	v_mul_f32_e32 v18, v16, v36
	v_fma_f32 v19, -v25, v18, v16
	v_fmac_f32_e32 v18, v19, v36
	v_fma_f32 v16, -v25, v18, v16
	v_div_fmas_f32 v16, v16, v36, v18
	v_div_fixup_f32 v60, v16, v17, s50
	v_lshlrev_b32_e32 v16, 16, v76
	v_and_b32_e32 v17, 0xffff0000, v76
	v_lshlrev_b32_e32 v18, 16, v77
	v_and_b32_e32 v19, 0xffff0000, v77
	v_pk_mul_f32 v[16:17], v[0:1], v[16:17]
	v_pk_mul_f32 v[18:19], v[2:3], v[18:19]
	v_pk_fma_f32 v[36:37], v[16:17], v[60:61], v[44:45] op_sel_hi:[1,0,1]
	v_pk_fma_f32 v[38:39], v[18:19], v[60:61], v[46:47] op_sel_hi:[1,0,1]
	v_lshlrev_b32_e32 v16, 16, v70
	v_and_b32_e32 v17, 0xffff0000, v70
	v_lshlrev_b32_e32 v18, 16, v71
	v_and_b32_e32 v19, 0xffff0000, v71
	v_pk_mul_f32 v[16:17], v[4:5], v[16:17]
	v_pk_mul_f32 v[18:19], v[6:7], v[18:19]
	v_pk_fma_f32 v[24:25], v[16:17], v[60:61], v[80:81] op_sel_hi:[1,0,1]
	v_pk_fma_f32 v[26:27], v[18:19], v[60:61], v[78:79] op_sel_hi:[1,0,1]
	v_lshlrev_b32_e32 v16, 16, v62
	v_and_b32_e32 v17, 0xffff0000, v62
	v_lshlrev_b32_e32 v18, 16, v63
	v_and_b32_e32 v19, 0xffff0000, v63
	v_lshlrev_b32_e32 v44, 16, v58
	v_and_b32_e32 v45, 0xffff0000, v58
	v_lshlrev_b32_e32 v46, 16, v59
	v_and_b32_e32 v47, 0xffff0000, v59
	v_pk_mul_f32 v[16:17], v[8:9], v[16:17]
	v_pk_mul_f32 v[18:19], v[10:11], v[18:19]
	v_pk_mul_f32 v[44:45], v[12:13], v[44:45]
	v_pk_mul_f32 v[46:47], v[14:15], v[46:47]
	v_pk_fma_f32 v[18:19], v[18:19], v[60:61], v[100:101] op_sel_hi:[1,0,1]
	v_pk_fma_f32 v[16:17], v[16:17], v[60:61], v[74:75] op_sel_hi:[1,0,1]
	v_pk_fma_f32 v[46:47], v[46:47], v[60:61], v[102:103] op_sel_hi:[1,0,1]
	s_andn2_b64 vcc, exec, s[72:73]
	v_pk_fma_f32 v[44:45], v[44:45], v[60:61], v[72:73] op_sel_hi:[1,0,1]
	s_cbranch_vccnz .LBB0_508
	v_lshl_add_u64 v[58:59], s[76:77], 0, v[48:49]
	global_store_dwordx4 v[58:59], v[36:39], off nt
	global_store_dwordx4 v[58:59], v[24:27], off offset:1024 nt
	global_store_dwordx4 v[58:59], v[16:19], off offset:2048 nt
	global_store_dwordx4 v[58:59], v[44:47], off offset:3072 nt
	s_waitcnt vmcnt(4)
.LBB0_508:
	s_andn2_b64 vcc, exec, s[74:75]
	s_cbranch_vccnz .Lrow_noxn
	v_pk_mul_f32 v[58:59], v[38:39], v[38:39]
	v_pk_mul_f32 v[62:63], v[36:37], v[36:37]
	s_nop 0
	v_pk_mov_b32 v[70:71], v[62:63], v[58:59] op_sel:[1,0]
	v_mov_b32_e32 v63, v59
	v_pk_add_f32 v[58:59], v[70:71], v[62:63]
	v_pk_mul_f32 v[62:63], v[26:27], v[26:27]
	v_pk_add_f32 v[58:59], v[58:59], v[58:59] op_sel_hi:[0,1]
	v_pk_mul_f32 v[70:71], v[24:25], v[24:25]
	v_mul_f32_e32 v58, v16, v16
	v_pk_mov_b32 v[72:73], v[70:71], v[62:63] op_sel:[1,0]
	v_mov_b32_e32 v71, v63
	v_pk_add_f32 v[62:63], v[72:73], v[70:71]
	v_pk_fma_f32 v[70:71], v[16:17], v[16:17], v[58:59] op_sel_hi:[1,1,0]
	v_mul_f32_e32 v58, v18, v18
	v_pk_add_f32 v[62:63], v[62:63], v[62:63] op_sel_hi:[0,1]
	v_pk_fma_f32 v[72:73], v[18:19], v[18:19], v[58:59] op_sel_hi:[1,1,0]
	v_mul_f32_e32 v70, v44, v44
	v_mul_f32_e32 v72, v45, v45
	v_mul_f32_e32 v58, v46, v46
	v_mul_f32_e32 v62, v47, v47
	v_pk_add_f32 v[70:71], v[70:71], v[72:73]
	v_pk_add_f32 v[58:59], v[58:59], v[62:63]
	s_nop 0
	v_pk_add_f32 v[58:59], v[70:71], v[58:59]
	s_nop 0
	v_add_f32_e32 v58, v58, v59
	ds_bpermute_b32 v59, v61, v58
	s_waitcnt lgkmcnt(0)
	v_add_f32_e32 v58, v58, v59
	ds_bpermute_b32 v59, v90, v58
	s_waitcnt lgkmcnt(0)
	v_add_f32_e32 v58, v58, v59
	ds_bpermute_b32 v59, v91, v58
	s_waitcnt lgkmcnt(0)
	v_add_f32_e32 v58, v58, v59
	ds_bpermute_b32 v59, v92, v58
	s_waitcnt lgkmcnt(0)
	v_add_f32_e32 v58, v58, v59
	ds_bpermute_b32 v59, v93, v58
	s_waitcnt lgkmcnt(0)
	v_add_f32_e32 v58, v58, v59
	ds_bpermute_b32 v59, v94, v58
	s_waitcnt lgkmcnt(0)
	v_add_f32_e32 v58, v58, v59
	v_fmamk_f32 v58, v58, 0x3a800000, v153
	v_mul_f32_e32 v59, 0x4f800000, v58
	v_cmp_gt_f32_e32 vcc, s33, v58
	s_nop 1
	v_cndmask_b32_e32 v60, v58, v59, vcc
	v_sqrt_f32_e32 v62, v60
	v_mov_b32_e32 v58, v36
	v_mov_b32_e32 v59, v38
	v_add_u32_e32 v36, -1, v62
	v_add_u32_e32 v38, 1, v62
	v_fma_f32 v63, -v36, v62, v60
	v_fma_f32 v70, -v38, v62, v60
	v_cmp_ge_f32_e64 s[0:1], 0, v63
	s_nop 1
	v_cndmask_b32_e64 v36, v62, v36, s[0:1]
	v_cmp_lt_f32_e64 s[0:1], 0, v70
	s_nop 1
	v_cndmask_b32_e64 v36, v36, v38, s[0:1]
	v_mul_f32_e32 v38, 0x37800000, v36
	v_cndmask_b32_e32 v36, v36, v38, vcc
	v_cmp_class_f32_e32 vcc, v60, v154
	v_mov_b32_e32 v38, v37
	s_nop 0
	v_cndmask_b32_e32 v36, v36, v60, vcc
	v_div_scale_f32 v60, s[0:1], v36, v36, 1.0
	v_rcp_f32_e32 v62, v60
	v_div_scale_f32 v37, vcc, 1.0, v36, 1.0
	v_fma_f32 v63, -v60, v62, 1.0
	v_fmac_f32_e32 v62, v63, v62
	v_mul_f32_e32 v63, v37, v62
	v_fma_f32 v70, -v60, v63, v37
	v_fmac_f32_e32 v63, v70, v62
	v_fma_f32 v37, -v60, v63, v37
	v_div_fmas_f32 v37, v37, v62, v63
	v_div_fixup_f32 v60, v37, v36, 1.0
	v_pk_mul_f32 v[58:59], v[58:59], v[60:61] op_sel_hi:[1,0]
	v_pk_mul_f32 v[38:39], v[38:39], v[60:61] op_sel_hi:[1,0]
	v_and_b32_sdwa v37, v59, v155 dst_sel:DWORD dst_unused:UNUSED_PAD src0_sel:WORD_1 src1_sel:DWORD
	v_and_b32_sdwa v62, v58, v155 dst_sel:DWORD dst_unused:UNUSED_PAD src0_sel:WORD_1 src1_sel:DWORD
	v_add3_u32 v58, v58, v62, s81
	v_add3_u32 v37, v59, v37, s81
	v_and_b32_sdwa v59, v39, v155 dst_sel:DWORD dst_unused:UNUSED_PAD src0_sel:WORD_1 src1_sel:DWORD
	v_and_b32_sdwa v62, v38, v155 dst_sel:DWORD dst_unused:UNUSED_PAD src0_sel:WORD_1 src1_sel:DWORD
	v_add3_u32 v39, v39, v59, s81
	v_add3_u32 v38, v38, v62, s81
	v_and_b32_e32 v39, 0xffff0000, v39
	v_and_b32_e32 v38, 0xffff0000, v38
	v_or_b32_sdwa v39, v39, v37 dst_sel:DWORD dst_unused:UNUSED_PAD src0_sel:DWORD src1_sel:WORD_1
	v_or_b32_sdwa v38, v38, v58 dst_sel:DWORD dst_unused:UNUSED_PAD src0_sel:DWORD src1_sel:WORD_1
	global_store_dwordx2 v[50:51], v[38:39], off
	v_mov_b32_e32 v38, v24
	v_mov_b32_e32 v39, v26
	v_pk_mul_f32 v[38:39], v[38:39], v[60:61] op_sel_hi:[1,0]
	v_mov_b32_e32 v26, v25
	v_pk_mul_f32 v[24:25], v[26:27], v[60:61] op_sel_hi:[1,0]
	v_and_b32_sdwa v27, v38, v155 dst_sel:DWORD dst_unused:UNUSED_PAD src0_sel:WORD_1 src1_sel:DWORD
	v_add3_u32 v27, v38, v27, s81
	v_and_b32_sdwa v37, v25, v155 dst_sel:DWORD dst_unused:UNUSED_PAD src0_sel:WORD_1 src1_sel:DWORD
	v_and_b32_sdwa v38, v24, v155 dst_sel:DWORD dst_unused:UNUSED_PAD src0_sel:WORD_1 src1_sel:DWORD
	v_and_b32_sdwa v26, v39, v155 dst_sel:DWORD dst_unused:UNUSED_PAD src0_sel:WORD_1 src1_sel:DWORD
	v_add3_u32 v25, v25, v37, s81
	v_add3_u32 v24, v24, v38, s81
	v_add3_u32 v26, v39, v26, s81
	v_and_b32_e32 v25, 0xffff0000, v25
	v_and_b32_e32 v24, 0xffff0000, v24
	v_or_b32_sdwa v25, v25, v26 dst_sel:DWORD dst_unused:UNUSED_PAD src0_sel:DWORD src1_sel:WORD_1
	v_or_b32_sdwa v24, v24, v27 dst_sel:DWORD dst_unused:UNUSED_PAD src0_sel:DWORD src1_sel:WORD_1
	global_store_dwordx2 v[50:51], v[24:25], off offset:512
	v_mov_b32_e32 v24, v16
	v_mov_b32_e32 v25, v18
	v_pk_mul_f32 v[24:25], v[24:25], v[60:61] op_sel_hi:[1,0]
	v_mov_b32_e32 v18, v17
	v_pk_mul_f32 v[16:17], v[18:19], v[60:61] op_sel_hi:[1,0]
	v_and_b32_sdwa v18, v25, v155 dst_sel:DWORD dst_unused:UNUSED_PAD src0_sel:WORD_1 src1_sel:DWORD
	v_and_b32_sdwa v19, v24, v155 dst_sel:DWORD dst_unused:UNUSED_PAD src0_sel:WORD_1 src1_sel:DWORD
	v_add3_u32 v19, v24, v19, s81
	v_add3_u32 v18, v25, v18, s81
	v_and_b32_sdwa v24, v17, v155 dst_sel:DWORD dst_unused:UNUSED_PAD src0_sel:WORD_1 src1_sel:DWORD
	v_and_b32_sdwa v25, v16, v155 dst_sel:DWORD dst_unused:UNUSED_PAD src0_sel:WORD_1 src1_sel:DWORD
	v_add3_u32 v17, v17, v24, s81
	v_add3_u32 v16, v16, v25, s81
	v_and_b32_e32 v17, 0xffff0000, v17
	v_and_b32_e32 v16, 0xffff0000, v16
	v_or_b32_sdwa v17, v17, v18 dst_sel:DWORD dst_unused:UNUSED_PAD src0_sel:DWORD src1_sel:WORD_1
	v_or_b32_sdwa v16, v16, v19 dst_sel:DWORD dst_unused:UNUSED_PAD src0_sel:DWORD src1_sel:WORD_1
	global_store_dwordx2 v[50:51], v[16:17], off offset:1024
	v_mov_b32_e32 v16, v44
	v_mov_b32_e32 v17, v46
	v_pk_mul_f32 v[16:17], v[16:17], v[60:61] op_sel_hi:[1,0]
	v_mov_b32_e32 v46, v45
	v_pk_mul_f32 v[18:19], v[46:47], v[60:61] op_sel_hi:[1,0]
	v_and_b32_sdwa v24, v17, v155 dst_sel:DWORD dst_unused:UNUSED_PAD src0_sel:WORD_1 src1_sel:DWORD
	v_and_b32_sdwa v25, v16, v155 dst_sel:DWORD dst_unused:UNUSED_PAD src0_sel:WORD_1 src1_sel:DWORD
	v_add3_u32 v16, v16, v25, s81
	v_add3_u32 v17, v17, v24, s81
	v_and_b32_sdwa v24, v19, v155 dst_sel:DWORD dst_unused:UNUSED_PAD src0_sel:WORD_1 src1_sel:DWORD
	v_and_b32_sdwa v25, v18, v155 dst_sel:DWORD dst_unused:UNUSED_PAD src0_sel:WORD_1 src1_sel:DWORD
	v_add3_u32 v19, v19, v24, s81
	v_add3_u32 v18, v18, v25, s81
	v_and_b32_e32 v19, 0xffff0000, v19
	v_and_b32_e32 v18, 0xffff0000, v18
	v_or_b32_sdwa v17, v19, v17 dst_sel:DWORD dst_unused:UNUSED_PAD src0_sel:DWORD src1_sel:WORD_1
	v_or_b32_sdwa v16, v18, v16 dst_sel:DWORD dst_unused:UNUSED_PAD src0_sel:DWORD src1_sel:WORD_1
	global_store_dwordx2 v[50:51], v[16:17], off offset:1536
	s_waitcnt vmcnt(4)
	s_and_saveexec_b64 s[0:1], s[42:43]
	s_cbranch_execz .LBB0_495
	v_readlane_b32 s52, v233, 5
	v_readlane_b32 s56, v233, 9
	v_readlane_b32 s57, v233, 10
	s_add_u32 s50, s56, s46
	s_addc_u32 s51, s57, s48
	v_readlane_b32 s53, v233, 6
	v_readlane_b32 s54, v233, 7
	v_readlane_b32 s55, v233, 8
	v_readlane_b32 s58, v233, 11
	v_readlane_b32 s59, v233, 12
	global_store_dword v97, v36, s[50:51]
	s_branch .LBB0_495
